# K-loop heads of the four GEMMs pinned to 64-byte boundaries (.p2align 6) on top of hand-written gate-up epilogue + w_down streaming + hand-written idle-round quantiser
# speedup vs baseline: 1.0212x; 1.0060x over previous
.LBB0_290:
	s_ashr_i32 s79, s78, 31
	s_lshl_b64 s[80:81], s[78:79], 21
	s_add_u32 s80, s22, s80
	s_addc_u32 s81, s23, s81
	s_and_b64 s[82:83], s[4:5], exec
	s_cselect_b32 s79, s81, s7
	s_cselect_b32 s88, s80, s6
	s_ashr_i32 s11, s10, 31
	s_lshl_b64 s[82:83], s[10:11], 21
	s_add_u32 s82, s8, s82
	s_addc_u32 s83, s9, s83
	s_and_b64 s[86:87], s[4:5], exec
	s_cselect_b32 s11, s83, s85
	s_cselect_b32 s89, s82, s84
	s_add_u32 s6, s6, 0x100080
	s_addc_u32 s7, s7, 0
	s_add_u32 s90, s84, 0x100
	v_mov_b32_e32 v50, 0
	s_addc_u32 s91, s85, 0
	s_mov_b32 vcc_lo, -2
	v_mov_b32_e32 v51, v50
	v_mov_b32_e32 v52, v50
	v_mov_b32_e32 v53, v50
	v_mov_b32_e32 v54, v50
	v_mov_b32_e32 v55, v50
	v_mov_b32_e32 v56, v50
	v_mov_b32_e32 v57, v50
	v_mov_b32_e32 v62, v50
	v_mov_b32_e32 v63, v50
	v_mov_b32_e32 v64, v50
	v_mov_b32_e32 v65, v50
	v_mov_b32_e32 v70, v50
	v_mov_b32_e32 v71, v50
	v_mov_b32_e32 v72, v50
	v_mov_b32_e32 v73, v50
	v_mov_b32_e32 v78, v50
	v_mov_b32_e32 v79, v50
	v_mov_b32_e32 v80, v50
	v_mov_b32_e32 v81, v50
	v_mov_b32_e32 v86, v50
	v_mov_b32_e32 v87, v50
	v_mov_b32_e32 v88, v50
	v_mov_b32_e32 v89, v50
	v_mov_b32_e32 v94, v50
	v_mov_b32_e32 v95, v50
	v_mov_b32_e32 v96, v50
	v_mov_b32_e32 v97, v50
	v_mov_b32_e32 v102, v50
	v_mov_b32_e32 v103, v50
	v_mov_b32_e32 v104, v50
	v_mov_b32_e32 v105, v50
	v_mov_b32_e32 v58, v50
	v_mov_b32_e32 v59, v50
	v_mov_b32_e32 v60, v50
	v_mov_b32_e32 v61, v50
	v_mov_b32_e32 v66, v50
	v_mov_b32_e32 v67, v50
	v_mov_b32_e32 v68, v50
	v_mov_b32_e32 v69, v50
	v_mov_b32_e32 v74, v50
	v_mov_b32_e32 v75, v50
	v_mov_b32_e32 v76, v50
	v_mov_b32_e32 v77, v50
	v_mov_b32_e32 v82, v50
	v_mov_b32_e32 v83, v50
	v_mov_b32_e32 v84, v50
	v_mov_b32_e32 v85, v50
	v_mov_b32_e32 v90, v50
	v_mov_b32_e32 v91, v50
	v_mov_b32_e32 v92, v50
	v_mov_b32_e32 v93, v50
	v_mov_b32_e32 v98, v50
	v_mov_b32_e32 v99, v50
	v_mov_b32_e32 v100, v50
	v_mov_b32_e32 v101, v50
	v_mov_b32_e32 v106, v50
	v_mov_b32_e32 v107, v50
	v_mov_b32_e32 v108, v50
	v_mov_b32_e32 v109, v50
	v_mov_b32_e32 v110, v50
	v_mov_b32_e32 v111, v50
	v_mov_b32_e32 v112, v50
	v_mov_b32_e32 v113, v50
	v_mov_b32_e32 v114, v50
	v_mov_b32_e32 v115, v50
	v_mov_b32_e32 v116, v50
	v_mov_b32_e32 v117, v50
	v_mov_b32_e32 v118, v50
	v_mov_b32_e32 v119, v50
	v_mov_b32_e32 v120, v50
	v_mov_b32_e32 v121, v50
	v_mov_b32_e32 v126, v50
	v_mov_b32_e32 v127, v50
	v_mov_b32_e32 v128, v50
	v_mov_b32_e32 v129, v50
	v_mov_b32_e32 v134, v50
	v_mov_b32_e32 v135, v50
	v_mov_b32_e32 v136, v50
	v_mov_b32_e32 v137, v50
	v_mov_b32_e32 v142, v50
	v_mov_b32_e32 v143, v50
	v_mov_b32_e32 v144, v50
	v_mov_b32_e32 v145, v50
	v_mov_b32_e32 v150, v50
	v_mov_b32_e32 v151, v50
	v_mov_b32_e32 v152, v50
	v_mov_b32_e32 v153, v50
	v_mov_b32_e32 v158, v50
	v_mov_b32_e32 v159, v50
	v_mov_b32_e32 v160, v50
	v_mov_b32_e32 v161, v50
	v_mov_b32_e32 v166, v50
	v_mov_b32_e32 v167, v50
	v_mov_b32_e32 v168, v50
	v_mov_b32_e32 v169, v50
	v_mov_b32_e32 v122, v50
	v_mov_b32_e32 v123, v50
	v_mov_b32_e32 v124, v50
	v_mov_b32_e32 v125, v50
	v_mov_b32_e32 v130, v50
	v_mov_b32_e32 v131, v50
	v_mov_b32_e32 v132, v50
	v_mov_b32_e32 v133, v50
	v_mov_b32_e32 v138, v50
	v_mov_b32_e32 v139, v50
	v_mov_b32_e32 v140, v50
	v_mov_b32_e32 v141, v50
	v_mov_b32_e32 v146, v50
	v_mov_b32_e32 v147, v50
	v_mov_b32_e32 v148, v50
	v_mov_b32_e32 v149, v50
	v_mov_b32_e32 v154, v50
	v_mov_b32_e32 v155, v50
	v_mov_b32_e32 v156, v50
	v_mov_b32_e32 v157, v50
	v_mov_b32_e32 v162, v50
	v_mov_b32_e32 v163, v50
	v_mov_b32_e32 v164, v50
	v_mov_b32_e32 v165, v50
	v_mov_b32_e32 v170, v50
	v_mov_b32_e32 v171, v50
	v_mov_b32_e32 v172, v50
	v_mov_b32_e32 v173, v50
	v_mov_b32_e32 v174, v50
	v_mov_b32_e32 v175, v50
	v_mov_b32_e32 v176, v50
	v_mov_b32_e32 v177, v50
	s_waitcnt vmcnt(0)
	.p2align 6

.LBB0_701:
	s_ashr_i32 s67, s66, 31
	s_lshl_b64 s[18:19], s[66:67], 21
	s_add_u32 s68, s6, s18
	s_addc_u32 s69, s7, s19
	s_and_b64 s[18:19], s[2:3], exec
	s_cselect_b32 s67, s69, s5
	s_cselect_b32 s82, s68, s4
	s_ashr_i32 s47, s46, 31
	s_lshl_b64 s[18:19], s[46:47], 21
	s_add_u32 s70, s64, s18
	s_addc_u32 s71, s65, s19
	s_and_b64 s[18:19], s[2:3], exec
	s_cselect_b32 s47, s71, s73
	s_cselect_b32 s83, s70, s72
	s_add_u32 s4, s4, 0x100080
	s_addc_u32 s5, s5, 0
	s_add_u32 s84, s72, 0x100
	v_mov_b32_e32 v2, 0
	s_addc_u32 s85, s73, 0
	s_mov_b32 s86, -2
	v_mov_b32_e32 v3, v2
	v_mov_b32_e32 v4, v2
	v_mov_b32_e32 v5, v2
	v_mov_b32_e32 v6, v2
	v_mov_b32_e32 v7, v2
	v_mov_b32_e32 v8, v2
	v_mov_b32_e32 v9, v2
	v_mov_b32_e32 v18, v2
	v_mov_b32_e32 v19, v2
	v_mov_b32_e32 v20, v2
	v_mov_b32_e32 v21, v2
	v_mov_b32_e32 v22, v2
	v_mov_b32_e32 v23, v2
	v_mov_b32_e32 v24, v2
	v_mov_b32_e32 v25, v2
	v_mov_b32_e32 v34, v2
	v_mov_b32_e32 v35, v2
	v_mov_b32_e32 v36, v2
	v_mov_b32_e32 v37, v2
	v_mov_b32_e32 v38, v2
	v_mov_b32_e32 v39, v2
	v_mov_b32_e32 v40, v2
	v_mov_b32_e32 v41, v2
	v_mov_b32_e32 v50, v2
	v_mov_b32_e32 v51, v2
	v_mov_b32_e32 v52, v2
	v_mov_b32_e32 v53, v2
	v_mov_b32_e32 v54, v2
	v_mov_b32_e32 v55, v2
	v_mov_b32_e32 v56, v2
	v_mov_b32_e32 v57, v2
	v_mov_b32_e32 v10, v2
	v_mov_b32_e32 v11, v2
	v_mov_b32_e32 v12, v2
	v_mov_b32_e32 v13, v2
	v_mov_b32_e32 v14, v2
	v_mov_b32_e32 v15, v2
	v_mov_b32_e32 v16, v2
	v_mov_b32_e32 v17, v2
	v_mov_b32_e32 v26, v2
	v_mov_b32_e32 v27, v2
	v_mov_b32_e32 v28, v2
	v_mov_b32_e32 v29, v2
	v_mov_b32_e32 v30, v2
	v_mov_b32_e32 v31, v2
	v_mov_b32_e32 v32, v2
	v_mov_b32_e32 v33, v2
	v_mov_b32_e32 v42, v2
	v_mov_b32_e32 v43, v2
	v_mov_b32_e32 v44, v2
	v_mov_b32_e32 v45, v2
	v_mov_b32_e32 v46, v2
	v_mov_b32_e32 v47, v2
	v_mov_b32_e32 v48, v2
	v_mov_b32_e32 v49, v2
	v_mov_b32_e32 v58, v2
	v_mov_b32_e32 v59, v2
	v_mov_b32_e32 v60, v2
	v_mov_b32_e32 v61, v2
	v_mov_b32_e32 v62, v2
	v_mov_b32_e32 v63, v2
	v_mov_b32_e32 v64, v2
	v_mov_b32_e32 v65, v2
	v_mov_b32_e32 v66, v2
	v_mov_b32_e32 v67, v2
	v_mov_b32_e32 v68, v2
	v_mov_b32_e32 v69, v2
	v_mov_b32_e32 v70, v2
	v_mov_b32_e32 v71, v2
	v_mov_b32_e32 v72, v2
	v_mov_b32_e32 v73, v2
	v_mov_b32_e32 v82, v2
	v_mov_b32_e32 v83, v2
	v_mov_b32_e32 v84, v2
	v_mov_b32_e32 v85, v2
	v_mov_b32_e32 v86, v2
	v_mov_b32_e32 v87, v2
	v_mov_b32_e32 v88, v2
	v_mov_b32_e32 v89, v2
	v_mov_b32_e32 v98, v2
	v_mov_b32_e32 v99, v2
	v_mov_b32_e32 v100, v2
	v_mov_b32_e32 v101, v2
	v_mov_b32_e32 v102, v2
	v_mov_b32_e32 v103, v2
	v_mov_b32_e32 v104, v2
	v_mov_b32_e32 v105, v2
	v_mov_b32_e32 v114, v2
	v_mov_b32_e32 v115, v2
	v_mov_b32_e32 v116, v2
	v_mov_b32_e32 v117, v2
	v_mov_b32_e32 v118, v2
	v_mov_b32_e32 v119, v2
	v_mov_b32_e32 v120, v2
	v_mov_b32_e32 v121, v2
	v_mov_b32_e32 v74, v2
	v_mov_b32_e32 v75, v2
	v_mov_b32_e32 v76, v2
	v_mov_b32_e32 v77, v2
	v_mov_b32_e32 v78, v2
	v_mov_b32_e32 v79, v2
	v_mov_b32_e32 v80, v2
	v_mov_b32_e32 v81, v2
	v_mov_b32_e32 v90, v2
	v_mov_b32_e32 v91, v2
	v_mov_b32_e32 v92, v2
	v_mov_b32_e32 v93, v2
	v_mov_b32_e32 v94, v2
	v_mov_b32_e32 v95, v2
	v_mov_b32_e32 v96, v2
	v_mov_b32_e32 v97, v2
	v_mov_b32_e32 v106, v2
	v_mov_b32_e32 v107, v2
	v_mov_b32_e32 v108, v2
	v_mov_b32_e32 v109, v2
	v_mov_b32_e32 v110, v2
	v_mov_b32_e32 v111, v2
	v_mov_b32_e32 v112, v2
	v_mov_b32_e32 v113, v2
	v_mov_b32_e32 v122, v2
	v_mov_b32_e32 v123, v2
	v_mov_b32_e32 v124, v2
	v_mov_b32_e32 v125, v2
	v_mov_b32_e32 v126, v2
	v_mov_b32_e32 v127, v2
	v_mov_b32_e32 v128, v2
	v_mov_b32_e32 v129, v2
	.p2align 6

.LBB0_910:
	s_ashr_i32 s43, s42, 31
	s_lshl_b64 s[18:19], s[42:43], 20
	s_add_u32 s44, s22, s18
	s_addc_u32 s45, s23, s19
	s_and_b64 s[18:19], s[6:7], exec
	s_cselect_b32 s13, s45, s67
	s_cselect_b32 s15, s44, s66
	s_ashr_i32 s41, s40, 31
	s_lshl_b64 s[18:19], s[40:41], 20
	s_add_u32 s46, s26, s18
	s_addc_u32 s47, s27, s19
	s_and_b64 s[18:19], s[6:7], exec
	s_cselect_b32 s24, s47, s69
	s_cselect_b32 s25, s46, s68
	s_add_u32 s66, s66, 0x80080
	s_addc_u32 s67, s67, 0
	s_add_u32 s41, s68, 0x100
	v_mov_b32_e32 v2, 0
	s_addc_u32 s43, s69, 0
	s_mov_b32 s60, -2
	v_mov_b32_e32 v3, v2
	v_mov_b32_e32 v4, v2
	v_mov_b32_e32 v5, v2
	v_mov_b32_e32 v10, v2
	v_mov_b32_e32 v11, v2
	v_mov_b32_e32 v12, v2
	v_mov_b32_e32 v13, v2
	v_mov_b32_e32 v18, v2
	v_mov_b32_e32 v19, v2
	v_mov_b32_e32 v20, v2
	v_mov_b32_e32 v21, v2
	v_mov_b32_e32 v26, v2
	v_mov_b32_e32 v27, v2
	v_mov_b32_e32 v28, v2
	v_mov_b32_e32 v29, v2
	v_mov_b32_e32 v34, v2
	v_mov_b32_e32 v35, v2
	v_mov_b32_e32 v36, v2
	v_mov_b32_e32 v37, v2
	v_mov_b32_e32 v42, v2
	v_mov_b32_e32 v43, v2
	v_mov_b32_e32 v44, v2
	v_mov_b32_e32 v45, v2
	v_mov_b32_e32 v54, v2
	v_mov_b32_e32 v55, v2
	v_mov_b32_e32 v56, v2
	v_mov_b32_e32 v57, v2
	v_mov_b32_e32 v66, v2
	v_mov_b32_e32 v67, v2
	v_mov_b32_e32 v68, v2
	v_mov_b32_e32 v69, v2
	v_mov_b32_e32 v6, v2
	v_mov_b32_e32 v7, v2
	v_mov_b32_e32 v8, v2
	v_mov_b32_e32 v9, v2
	v_mov_b32_e32 v14, v2
	v_mov_b32_e32 v15, v2
	v_mov_b32_e32 v16, v2
	v_mov_b32_e32 v17, v2
	v_mov_b32_e32 v22, v2
	v_mov_b32_e32 v23, v2
	v_mov_b32_e32 v24, v2
	v_mov_b32_e32 v25, v2
	v_mov_b32_e32 v30, v2
	v_mov_b32_e32 v31, v2
	v_mov_b32_e32 v32, v2
	v_mov_b32_e32 v33, v2
	v_mov_b32_e32 v38, v2
	v_mov_b32_e32 v39, v2
	v_mov_b32_e32 v40, v2
	v_mov_b32_e32 v41, v2
	v_mov_b32_e32 v46, v2
	v_mov_b32_e32 v47, v2
	v_mov_b32_e32 v48, v2
	v_mov_b32_e32 v49, v2
	v_mov_b32_e32 v58, v2
	v_mov_b32_e32 v59, v2
	v_mov_b32_e32 v60, v2
	v_mov_b32_e32 v61, v2
	v_mov_b32_e32 v70, v2
	v_mov_b32_e32 v71, v2
	v_mov_b32_e32 v72, v2
	v_mov_b32_e32 v73, v2
	v_mov_b32_e32 v74, v2
	v_mov_b32_e32 v75, v2
	v_mov_b32_e32 v76, v2
	v_mov_b32_e32 v77, v2
	v_mov_b32_e32 v82, v2
	v_mov_b32_e32 v83, v2
	v_mov_b32_e32 v84, v2
	v_mov_b32_e32 v85, v2
	v_mov_b32_e32 v90, v2
	v_mov_b32_e32 v91, v2
	v_mov_b32_e32 v92, v2
	v_mov_b32_e32 v93, v2
	v_mov_b32_e32 v98, v2
	v_mov_b32_e32 v99, v2
	v_mov_b32_e32 v100, v2
	v_mov_b32_e32 v101, v2
	v_mov_b32_e32 v106, v2
	v_mov_b32_e32 v107, v2
	v_mov_b32_e32 v108, v2
	v_mov_b32_e32 v109, v2
	v_mov_b32_e32 v114, v2
	v_mov_b32_e32 v115, v2
	v_mov_b32_e32 v116, v2
	v_mov_b32_e32 v117, v2
	v_mov_b32_e32 v122, v2
	v_mov_b32_e32 v123, v2
	v_mov_b32_e32 v124, v2
	v_mov_b32_e32 v125, v2
	v_mov_b32_e32 v130, v2
	v_mov_b32_e32 v131, v2
	v_mov_b32_e32 v132, v2
	v_mov_b32_e32 v133, v2
	v_mov_b32_e32 v78, v2
	v_mov_b32_e32 v79, v2
	v_mov_b32_e32 v80, v2
	v_mov_b32_e32 v81, v2
	v_mov_b32_e32 v86, v2
	v_mov_b32_e32 v87, v2
	v_mov_b32_e32 v88, v2
	v_mov_b32_e32 v89, v2
	v_mov_b32_e32 v94, v2
	v_mov_b32_e32 v95, v2
	v_mov_b32_e32 v96, v2
	v_mov_b32_e32 v97, v2
	v_mov_b32_e32 v102, v2
	v_mov_b32_e32 v103, v2
	v_mov_b32_e32 v104, v2
	v_mov_b32_e32 v105, v2
	v_mov_b32_e32 v110, v2
	v_mov_b32_e32 v111, v2
	v_mov_b32_e32 v112, v2
	v_mov_b32_e32 v113, v2
	v_mov_b32_e32 v118, v2
	v_mov_b32_e32 v119, v2
	v_mov_b32_e32 v120, v2
	v_mov_b32_e32 v121, v2
	v_mov_b32_e32 v126, v2
	v_mov_b32_e32 v127, v2
	v_mov_b32_e32 v128, v2
	v_mov_b32_e32 v129, v2
	v_mov_b32_e32 v134, v2
	v_mov_b32_e32 v135, v2
	v_mov_b32_e32 v136, v2
	v_mov_b32_e32 v137, v2
	.p2align 6

.LBB0_1081:
	s_add_u32 s40, s40, 0x158080
	s_addc_u32 s41, s41, 0
	s_add_u32 s73, s42, 0x100
	v_mov_b32_e32 v2, 0
	s_addc_u32 s74, s43, 0
	s_mov_b32 s75, -2
	v_mov_b32_e32 v3, v2
	v_mov_b32_e32 v4, v2
	v_mov_b32_e32 v5, v2
	v_mov_b32_e32 v6, v2
	v_mov_b32_e32 v7, v2
	v_mov_b32_e32 v8, v2
	v_mov_b32_e32 v9, v2
	v_mov_b32_e32 v14, v2
	v_mov_b32_e32 v15, v2
	v_mov_b32_e32 v16, v2
	v_mov_b32_e32 v17, v2
	v_mov_b32_e32 v22, v2
	v_mov_b32_e32 v23, v2
	v_mov_b32_e32 v24, v2
	v_mov_b32_e32 v25, v2
	v_mov_b32_e32 v30, v2
	v_mov_b32_e32 v31, v2
	v_mov_b32_e32 v32, v2
	v_mov_b32_e32 v33, v2
	v_mov_b32_e32 v38, v2
	v_mov_b32_e32 v39, v2
	v_mov_b32_e32 v40, v2
	v_mov_b32_e32 v41, v2
	v_mov_b32_e32 v46, v2
	v_mov_b32_e32 v47, v2
	v_mov_b32_e32 v48, v2
	v_mov_b32_e32 v49, v2
	v_mov_b32_e32 v54, v2
	v_mov_b32_e32 v55, v2
	v_mov_b32_e32 v56, v2
	v_mov_b32_e32 v57, v2
	v_mov_b32_e32 v10, v2
	v_mov_b32_e32 v11, v2
	v_mov_b32_e32 v12, v2
	v_mov_b32_e32 v13, v2
	v_mov_b32_e32 v18, v2
	v_mov_b32_e32 v19, v2
	v_mov_b32_e32 v20, v2
	v_mov_b32_e32 v21, v2
	v_mov_b32_e32 v26, v2
	v_mov_b32_e32 v27, v2
	v_mov_b32_e32 v28, v2
	v_mov_b32_e32 v29, v2
	v_mov_b32_e32 v34, v2
	v_mov_b32_e32 v35, v2
	v_mov_b32_e32 v36, v2
	v_mov_b32_e32 v37, v2
	v_mov_b32_e32 v42, v2
	v_mov_b32_e32 v43, v2
	v_mov_b32_e32 v44, v2
	v_mov_b32_e32 v45, v2
	v_mov_b32_e32 v50, v2
	v_mov_b32_e32 v51, v2
	v_mov_b32_e32 v52, v2
	v_mov_b32_e32 v53, v2
	v_mov_b32_e32 v58, v2
	v_mov_b32_e32 v59, v2
	v_mov_b32_e32 v60, v2
	v_mov_b32_e32 v61, v2
	v_mov_b32_e32 v62, v2
	v_mov_b32_e32 v63, v2
	v_mov_b32_e32 v64, v2
	v_mov_b32_e32 v65, v2
	v_mov_b32_e32 v66, v2
	v_mov_b32_e32 v67, v2
	v_mov_b32_e32 v68, v2
	v_mov_b32_e32 v69, v2
	v_mov_b32_e32 v70, v2
	v_mov_b32_e32 v71, v2
	v_mov_b32_e32 v72, v2
	v_mov_b32_e32 v73, v2
	v_mov_b32_e32 v82, v2
	v_mov_b32_e32 v83, v2
	v_mov_b32_e32 v84, v2
	v_mov_b32_e32 v85, v2
	v_mov_b32_e32 v86, v2
	v_mov_b32_e32 v87, v2
	v_mov_b32_e32 v88, v2
	v_mov_b32_e32 v89, v2
	v_mov_b32_e32 v98, v2
	v_mov_b32_e32 v99, v2
	v_mov_b32_e32 v100, v2
	v_mov_b32_e32 v101, v2
	v_mov_b32_e32 v102, v2
	v_mov_b32_e32 v103, v2
	v_mov_b32_e32 v104, v2
	v_mov_b32_e32 v105, v2
	v_mov_b32_e32 v110, v2
	v_mov_b32_e32 v111, v2
	v_mov_b32_e32 v112, v2
	v_mov_b32_e32 v113, v2
	v_mov_b32_e32 v118, v2
	v_mov_b32_e32 v119, v2
	v_mov_b32_e32 v120, v2
	v_mov_b32_e32 v121, v2
	v_mov_b32_e32 v74, v2
	v_mov_b32_e32 v75, v2
	v_mov_b32_e32 v76, v2
	v_mov_b32_e32 v77, v2
	v_mov_b32_e32 v78, v2
	v_mov_b32_e32 v79, v2
	v_mov_b32_e32 v80, v2
	v_mov_b32_e32 v81, v2
	v_mov_b32_e32 v90, v2
	v_mov_b32_e32 v91, v2
	v_mov_b32_e32 v92, v2
	v_mov_b32_e32 v93, v2
	v_mov_b32_e32 v94, v2
	v_mov_b32_e32 v95, v2
	v_mov_b32_e32 v96, v2
	v_mov_b32_e32 v97, v2
	v_mov_b32_e32 v106, v2
	v_mov_b32_e32 v107, v2
	v_mov_b32_e32 v108, v2
	v_mov_b32_e32 v109, v2
	v_mov_b32_e32 v114, v2
	v_mov_b32_e32 v115, v2
	v_mov_b32_e32 v116, v2
	v_mov_b32_e32 v117, v2
	v_mov_b32_e32 v122, v2
	v_mov_b32_e32 v123, v2
	v_mov_b32_e32 v124, v2
	v_mov_b32_e32 v125, v2
	v_mov_b32_e32 v126, v2
	v_mov_b32_e32 v127, v2
	v_mov_b32_e32 v128, v2
	v_mov_b32_e32 v129, v2
	.p2align 6
